# h3 ctx direct conv: the 8 u-row loads of each 8-step block issued before the conditional filter-tap loads (one global round trip per block instead of two)
# baseline (speedup 1.0000x reference)
; __device__ __forceinline__ void h3_longconv(const KQ p_in, int o, bool ctx_full, unsigned char* smem) {
;     ...
;         for (int idx = blockIdx.x * 512 + tid; idx < (TC / 8) * D; idx += gridDim.x * 512) {
;             const int d = idx & 1023, og = idx >> 10;
;             const int bb = og >> 5, n0 = (og & 31) * 8, tb = TL + bb * CL;
;             const float* up = VX + (size_t)tb * D + d;
;             float acc[8];
; #pragma unroll
;             for (int j = 0; j < 8; ++j) acc[j] = 0.f;
; #pragma unroll 1
;             for (int mb = 0; mb < CL; mb += 8) {
;                 float kk[15], uu[8];
; #pragma unroll
;                 for (int q = 0; q < 15; ++q) { const int lag = n0 - mb - 7 + q;
;                     kk[q] = (lag >= 0) ? ((lag < CL) ? kf[(size_t)lag * D + d] : 0.f) : ((-lag < CL) ? kf[(size_t)(CL - lag) * D + d] : 0.f); }
; #pragma unroll
;                 for (int u = 0; u < 8; ++u) uu[u] = up[(size_t)(mb + u) * D];
; #pragma unroll
;                 for (int u = 0; u < 8; ++u)
; #pragma unroll
;                     for (int j = 0; j < 8; ++j) acc[j] += uu[u] * kk[7 - u + j];
.LBB0_525:
	v_ashrrev_i32_e32 v2, 7, v1
	v_and_b32_e32 v2, 0xffffff00, v2
	v_add_u32_e32 v10, 0x4000, v2
	v_bfe_u32 v0, v1, 10, 5
	v_ashrrev_i32_e32 v11, 31, v10
	v_lshl_add_u32 v9, v0, 3, -7
	v_lshlrev_b32_e32 v0, 15, v0
	v_and_b32_e32 v4, 0x3ff, v41
	v_lshlrev_b64 v[2:3], 12, v[10:11]
	v_sub_u32_e32 v8, 0, v0
	v_or_b32_e32 v43, 0x7000, v0
	v_and_b32_e32 v0, 0x3ff, v1
	v_lshrrev_b32_e32 v5, 7, v1
	v_lshl_or_b32 v2, v4, 2, v2
	v_and_b32_e32 v11, 0xf8, v5
	v_lshlrev_b32_e32 v144, 2, v0
	v_lshl_add_u64 v[16:17], s[4:5], 0, v[2:3]
	v_mov_b32_e32 v2, 0
	s_mov_b32 s2, 0
	v_add_u32_e32 v45, -7, v11
	v_lshl_add_u64 v[12:13], s[16:17], 0, v[144:145]
	s_mov_b32 s30, -8
	s_mov_b64 s[20:21], 0
	v_mov_b32_e32 v3, v2
	v_mov_b32_e32 v4, v2
	v_mov_b32_e32 v5, v2
	v_mov_b32_e32 v6, v2
	v_mov_b32_e32 v7, v2
	v_mov_b32_e32 v14, v2
	v_mov_b32_e32 v15, v2
	s_mov_b32 s98, 0x131b5000
	s_mov_b32 s99, 0
	s_mov_b32 s100, 0x2000
	s_mov_b32 s101, 0
	s_branch .LBB0_527
.LBB0_526:
	s_or_b64 exec, exec, s[22:23]
	s_waitcnt vmcnt(0) lgkmcnt(0)
	v_mov_b32_e32 v28, v33
	v_mov_b32_e32 v30, v29
	v_mov_b32_e32 v26, v31
	v_mov_b32_e32 v24, v27
	v_mov_b32_e32 v22, v25
	v_mov_b32_e32 v20, v23
	v_mov_b32_e32 v18, v21
	s_add_i32 s2, s2, 8
	s_add_u32 s20, s20, 0x8000
	s_addc_u32 s21, s21, 0
	s_add_i32 s30, s30, 8
	v_add_u32_e32 v9, -8, v9
	s_cmpk_gt_u32 s30, 0xf7
	s_waitcnt lgkmcnt(0)
	s_waitcnt vmcnt(7)
	v_pk_fma_f32 v[14:15], v[32:33], v[210:211], v[14:15] op_sel_hi:[1,0,1]
	v_pk_fma_f32 v[6:7], v[34:35], v[210:211], v[6:7] op_sel_hi:[1,0,1]
	v_pk_fma_f32 v[4:5], v[36:37], v[210:211], v[4:5] op_sel_hi:[1,0,1]
	v_pk_fma_f32 v[2:3], v[38:39], v[210:211], v[2:3] op_sel_hi:[1,0,1]
	s_waitcnt vmcnt(6)
	v_pk_fma_f32 v[14:15], v[28:29], v[212:213], v[14:15] op_sel_hi:[1,0,1]
	s_nop 0
	s_waitcnt vmcnt(5)
	v_pk_fma_f32 v[14:15], v[30:31], v[214:215], v[14:15] op_sel_hi:[1,0,1]
	s_nop 0
	s_waitcnt vmcnt(4)
	v_pk_fma_f32 v[14:15], v[26:27], v[216:217], v[14:15] op_sel_hi:[1,0,1]
	s_nop 0
	s_waitcnt vmcnt(3)
	v_pk_fma_f32 v[14:15], v[24:25], v[218:219], v[14:15] op_sel_hi:[1,0,1]
	s_nop 0
	s_waitcnt vmcnt(2)
	v_pk_fma_f32 v[14:15], v[22:23], v[220:221], v[14:15] op_sel_hi:[1,0,1]
	s_nop 0
	s_waitcnt vmcnt(1)
	v_pk_fma_f32 v[14:15], v[20:21], v[222:223], v[14:15] op_sel_hi:[1,0,1]
	v_mov_b32_e32 v20, v37
	v_mov_b32_e32 v21, v34
	s_waitcnt vmcnt(0)
	v_pk_fma_f32 v[14:15], v[18:19], v[224:225], v[14:15] op_sel_hi:[1,0,1]
	v_mov_b32_e32 v18, v35
	v_mov_b32_e32 v19, v32
	v_pk_fma_f32 v[6:7], v[18:19], v[212:213], v[6:7] op_sel_hi:[1,0,1]
	v_pk_fma_f32 v[4:5], v[20:21], v[212:213], v[4:5] op_sel_hi:[1,0,1]
	v_pk_fma_f32 v[6:7], v[32:33], v[214:215], v[6:7] op_sel_hi:[1,0,1]
	v_pk_fma_f32 v[4:5], v[34:35], v[214:215], v[4:5] op_sel_hi:[1,0,1]
	v_pk_fma_f32 v[6:7], v[28:29], v[216:217], v[6:7] op_sel_hi:[1,0,1]
	v_pk_fma_f32 v[4:5], v[18:19], v[216:217], v[4:5] op_sel_hi:[1,0,1]
	v_pk_fma_f32 v[6:7], v[30:31], v[218:219], v[6:7] op_sel_hi:[1,0,1]
	v_pk_fma_f32 v[4:5], v[32:33], v[218:219], v[4:5] op_sel_hi:[1,0,1]
	v_pk_fma_f32 v[6:7], v[26:27], v[220:221], v[6:7] op_sel_hi:[1,0,1]
	v_pk_fma_f32 v[4:5], v[28:29], v[220:221], v[4:5] op_sel_hi:[1,0,1]
	v_pk_fma_f32 v[6:7], v[24:25], v[222:223], v[6:7] op_sel_hi:[1,0,1]
	v_pk_fma_f32 v[4:5], v[30:31], v[222:223], v[4:5] op_sel_hi:[1,0,1]
	v_pk_fma_f32 v[6:7], v[22:23], v[224:225], v[6:7] op_sel_hi:[1,0,1]
	v_mov_b32_e32 v22, v39
	v_mov_b32_e32 v23, v36
	v_pk_fma_f32 v[2:3], v[22:23], v[212:213], v[2:3] op_sel_hi:[1,0,1]
	v_pk_fma_f32 v[4:5], v[26:27], v[224:225], v[4:5] op_sel_hi:[1,0,1]
	v_pk_fma_f32 v[2:3], v[36:37], v[214:215], v[2:3] op_sel_hi:[1,0,1]
	s_nop 0
	v_pk_fma_f32 v[2:3], v[20:21], v[216:217], v[2:3] op_sel_hi:[1,0,1]
	s_nop 0
	v_pk_fma_f32 v[2:3], v[34:35], v[218:219], v[2:3] op_sel_hi:[1,0,1]
	s_nop 0
	v_pk_fma_f32 v[2:3], v[18:19], v[220:221], v[2:3] op_sel_hi:[1,0,1]
	s_nop 0
	v_pk_fma_f32 v[2:3], v[32:33], v[222:223], v[2:3] op_sel_hi:[1,0,1]
	v_add_u32_e32 v43, 0xffff8000, v43
	v_pk_fma_f32 v[2:3], v[28:29], v[224:225], v[2:3] op_sel_hi:[1,0,1]
	s_cbranch_scc1 .LBB0_524
.LBB0_527:
	v_lshl_add_u64 v[208:209], v[16:17], 0, s[20:21]
	v_lshl_add_u64 v[208:209], v[208:209], 0, s[98:99]
	v_lshl_add_u64 v[226:227], v[208:209], 0, s[100:101]
	v_lshl_add_u64 v[228:229], v[226:227], 0, s[100:101]
	v_lshl_add_u64 v[230:231], v[228:229], 0, s[100:101]
	global_load_dword v210, v[208:209], off offset:-4096
	global_load_dword v212, v[208:209], off
	global_load_dword v214, v[226:227], off offset:-4096
	global_load_dword v216, v[226:227], off
	global_load_dword v218, v[228:229], off offset:-4096
	global_load_dword v220, v[228:229], off
	global_load_dword v222, v[230:231], off offset:-4096
	global_load_dword v224, v[230:231], off
	v_cmp_gt_i32_e32 vcc, 0, v9
	s_mov_b64 s[22:23], 0
	s_and_saveexec_b64 s[0:1], vcc
	s_xor_b64 s[24:25], exec, s[0:1]
	s_cbranch_execz .LBB0_616
	v_cmp_lt_u32_e64 s[0:1], s57, v9
	s_and_saveexec_b64 s[26:27], s[0:1]
	s_xor_b64 s[0:1], exec, s[26:27]
	v_add_u32_e32 v18, s20, v8
	s_mov_b64 s[22:23], exec
	v_add_u32_e32 v144, 0x107000, v18
	s_or_b64 exec, exec, s[0:1]
	s_and_b64 s[22:23], s[22:23], exec
	s_or_saveexec_b64 s[24:25], s[24:25]
	v_subrev_u32_e32 v18, s2, v45
	s_xor_b64 exec, exec, s[24:25]
	s_cbranch_execnz .LBB0_617
